# GEMM unit loop: deleted the redundant second accumulator-zeroing block (128 v_mov per unit per wave) in all 4 GEMM instances
# baseline (speedup 1.0000x reference)
.LBB0_45:
	v_mov_b32_e32 v123, 0
	s_andn2_b64 vcc, exec, s[14:15]
	v_mov_b32_e32 v122, v123
	v_mov_b32_e32 v121, v123
	v_mov_b32_e32 v120, v123
	v_mov_b32_e32 v127, v123
	v_mov_b32_e32 v126, v123
	v_mov_b32_e32 v125, v123
	v_mov_b32_e32 v124, v123
	v_mov_b32_e32 v111, v123
	v_mov_b32_e32 v110, v123
	v_mov_b32_e32 v109, v123
	v_mov_b32_e32 v108, v123
	v_mov_b32_e32 v107, v123
	v_mov_b32_e32 v106, v123
	v_mov_b32_e32 v105, v123
	v_mov_b32_e32 v104, v123
	v_mov_b32_e32 v95, v123
	v_mov_b32_e32 v94, v123
	v_mov_b32_e32 v93, v123
	v_mov_b32_e32 v92, v123
	v_mov_b32_e32 v91, v123
	v_mov_b32_e32 v90, v123
	v_mov_b32_e32 v89, v123
	v_mov_b32_e32 v88, v123
	v_mov_b32_e32 v79, v123
	v_mov_b32_e32 v78, v123
	v_mov_b32_e32 v77, v123
	v_mov_b32_e32 v76, v123
	v_mov_b32_e32 v75, v123
	v_mov_b32_e32 v74, v123
	v_mov_b32_e32 v73, v123
	v_mov_b32_e32 v72, v123
	v_mov_b32_e32 v119, v123
	v_mov_b32_e32 v118, v123
	v_mov_b32_e32 v117, v123
	v_mov_b32_e32 v116, v123
	v_mov_b32_e32 v115, v123
	v_mov_b32_e32 v114, v123
	v_mov_b32_e32 v113, v123
	v_mov_b32_e32 v112, v123
	v_mov_b32_e32 v103, v123
	v_mov_b32_e32 v102, v123
	v_mov_b32_e32 v101, v123
	v_mov_b32_e32 v100, v123
	v_mov_b32_e32 v99, v123
	v_mov_b32_e32 v98, v123
	v_mov_b32_e32 v97, v123
	v_mov_b32_e32 v96, v123
	v_mov_b32_e32 v87, v123
	v_mov_b32_e32 v86, v123
	v_mov_b32_e32 v85, v123
	v_mov_b32_e32 v84, v123
	v_mov_b32_e32 v83, v123
	v_mov_b32_e32 v82, v123
	v_mov_b32_e32 v81, v123
	v_mov_b32_e32 v80, v123
	v_mov_b32_e32 v71, v123
	v_mov_b32_e32 v70, v123
	v_mov_b32_e32 v69, v123
	v_mov_b32_e32 v68, v123
	v_mov_b32_e32 v67, v123
	v_mov_b32_e32 v66, v123
	v_mov_b32_e32 v65, v123
	v_mov_b32_e32 v64, v123
	v_mov_b32_e32 v63, v123
	v_mov_b32_e32 v62, v123
	v_mov_b32_e32 v61, v123
	v_mov_b32_e32 v60, v123
	v_mov_b32_e32 v59, v123
	v_mov_b32_e32 v58, v123
	v_mov_b32_e32 v57, v123
	v_mov_b32_e32 v56, v123
	v_mov_b32_e32 v47, v123
	v_mov_b32_e32 v46, v123
	v_mov_b32_e32 v45, v123
	v_mov_b32_e32 v44, v123
	v_mov_b32_e32 v43, v123
	v_mov_b32_e32 v42, v123
	v_mov_b32_e32 v41, v123
	v_mov_b32_e32 v40, v123
	v_mov_b32_e32 v31, v123
	v_mov_b32_e32 v30, v123
	v_mov_b32_e32 v29, v123
	v_mov_b32_e32 v28, v123
	v_mov_b32_e32 v27, v123
	v_mov_b32_e32 v26, v123
	v_mov_b32_e32 v25, v123
	v_mov_b32_e32 v24, v123
	v_mov_b32_e32 v15, v123
	v_mov_b32_e32 v14, v123
	v_mov_b32_e32 v13, v123
	v_mov_b32_e32 v12, v123
	v_mov_b32_e32 v11, v123
	v_mov_b32_e32 v10, v123
	v_mov_b32_e32 v9, v123
	v_mov_b32_e32 v8, v123
	v_mov_b32_e32 v55, v123
	v_mov_b32_e32 v54, v123
	v_mov_b32_e32 v53, v123
	v_mov_b32_e32 v52, v123
	v_mov_b32_e32 v51, v123
	v_mov_b32_e32 v50, v123
	v_mov_b32_e32 v49, v123
	v_mov_b32_e32 v48, v123
	v_mov_b32_e32 v39, v123
	v_mov_b32_e32 v38, v123
	v_mov_b32_e32 v37, v123
	v_mov_b32_e32 v36, v123
	v_mov_b32_e32 v35, v123
	v_mov_b32_e32 v34, v123
	v_mov_b32_e32 v33, v123
	v_mov_b32_e32 v32, v123
	v_mov_b32_e32 v23, v123
	v_mov_b32_e32 v22, v123
	v_mov_b32_e32 v21, v123
	v_mov_b32_e32 v20, v123
	v_mov_b32_e32 v19, v123
	v_mov_b32_e32 v18, v123
	v_mov_b32_e32 v17, v123
	v_mov_b32_e32 v16, v123
	v_mov_b32_e32 v7, v123
	v_mov_b32_e32 v6, v123
	v_mov_b32_e32 v5, v123
	v_mov_b32_e32 v4, v123
	v_mov_b32_e32 v3, v123
	v_mov_b32_e32 v2, v123
	v_mov_b32_e32 v1, v123
	v_mov_b32_e32 v0, v123
	s_cbranch_vccnz .LBB0_49
	s_add_u32 s0, s28, 0x80
	s_addc_u32 s1, s29, 0
	s_add_u32 s28, s26, 0x100
	s_addc_u32 s29, s27, 0
	s_mov_b32 s26, 0

.LBB0_101:
	v_mov_b32_e32 v127, 0
	s_andn2_b64 vcc, exec, s[14:15]
	v_mov_b32_e32 v126, v127
	v_mov_b32_e32 v125, v127
	v_mov_b32_e32 v124, v127
	v_mov_b32_e32 v119, v127
	v_mov_b32_e32 v118, v127
	v_mov_b32_e32 v117, v127
	v_mov_b32_e32 v116, v127
	v_mov_b32_e32 v111, v127
	v_mov_b32_e32 v110, v127
	v_mov_b32_e32 v109, v127
	v_mov_b32_e32 v108, v127
	v_mov_b32_e32 v103, v127
	v_mov_b32_e32 v102, v127
	v_mov_b32_e32 v101, v127
	v_mov_b32_e32 v100, v127
	v_mov_b32_e32 v95, v127
	v_mov_b32_e32 v94, v127
	v_mov_b32_e32 v93, v127
	v_mov_b32_e32 v92, v127
	v_mov_b32_e32 v87, v127
	v_mov_b32_e32 v86, v127
	v_mov_b32_e32 v85, v127
	v_mov_b32_e32 v84, v127
	v_mov_b32_e32 v79, v127
	v_mov_b32_e32 v78, v127
	v_mov_b32_e32 v77, v127
	v_mov_b32_e32 v76, v127
	v_mov_b32_e32 v71, v127
	v_mov_b32_e32 v70, v127
	v_mov_b32_e32 v69, v127
	v_mov_b32_e32 v68, v127
	v_mov_b32_e32 v123, v127
	v_mov_b32_e32 v122, v127
	v_mov_b32_e32 v121, v127
	v_mov_b32_e32 v120, v127
	v_mov_b32_e32 v115, v127
	v_mov_b32_e32 v114, v127
	v_mov_b32_e32 v113, v127
	v_mov_b32_e32 v112, v127
	v_mov_b32_e32 v107, v127
	v_mov_b32_e32 v106, v127
	v_mov_b32_e32 v105, v127
	v_mov_b32_e32 v104, v127
	v_mov_b32_e32 v99, v127
	v_mov_b32_e32 v98, v127
	v_mov_b32_e32 v97, v127
	v_mov_b32_e32 v96, v127
	v_mov_b32_e32 v91, v127
	v_mov_b32_e32 v90, v127
	v_mov_b32_e32 v89, v127
	v_mov_b32_e32 v88, v127
	v_mov_b32_e32 v83, v127
	v_mov_b32_e32 v82, v127
	v_mov_b32_e32 v81, v127
	v_mov_b32_e32 v80, v127
	v_mov_b32_e32 v75, v127
	v_mov_b32_e32 v74, v127
	v_mov_b32_e32 v73, v127
	v_mov_b32_e32 v72, v127
	v_mov_b32_e32 v67, v127
	v_mov_b32_e32 v66, v127
	v_mov_b32_e32 v65, v127
	v_mov_b32_e32 v64, v127
	v_mov_b32_e32 v63, v127
	v_mov_b32_e32 v62, v127
	v_mov_b32_e32 v61, v127
	v_mov_b32_e32 v60, v127
	v_mov_b32_e32 v55, v127
	v_mov_b32_e32 v54, v127
	v_mov_b32_e32 v53, v127
	v_mov_b32_e32 v52, v127
	v_mov_b32_e32 v47, v127
	v_mov_b32_e32 v46, v127
	v_mov_b32_e32 v45, v127
	v_mov_b32_e32 v44, v127
	v_mov_b32_e32 v39, v127
	v_mov_b32_e32 v38, v127
	v_mov_b32_e32 v37, v127
	v_mov_b32_e32 v36, v127
	v_mov_b32_e32 v31, v127
	v_mov_b32_e32 v30, v127
	v_mov_b32_e32 v29, v127
	v_mov_b32_e32 v28, v127
	v_mov_b32_e32 v23, v127
	v_mov_b32_e32 v22, v127
	v_mov_b32_e32 v21, v127
	v_mov_b32_e32 v20, v127
	v_mov_b32_e32 v15, v127
	v_mov_b32_e32 v14, v127
	v_mov_b32_e32 v13, v127
	v_mov_b32_e32 v12, v127
	v_mov_b32_e32 v7, v127
	v_mov_b32_e32 v6, v127
	v_mov_b32_e32 v5, v127
	v_mov_b32_e32 v4, v127
	v_mov_b32_e32 v59, v127
	v_mov_b32_e32 v58, v127
	v_mov_b32_e32 v57, v127
	v_mov_b32_e32 v56, v127
	v_mov_b32_e32 v51, v127
	v_mov_b32_e32 v50, v127
	v_mov_b32_e32 v49, v127
	v_mov_b32_e32 v48, v127
	v_mov_b32_e32 v43, v127
	v_mov_b32_e32 v42, v127
	v_mov_b32_e32 v41, v127
	v_mov_b32_e32 v40, v127
	v_mov_b32_e32 v35, v127
	v_mov_b32_e32 v34, v127
	v_mov_b32_e32 v33, v127
	v_mov_b32_e32 v32, v127
	v_mov_b32_e32 v27, v127
	v_mov_b32_e32 v26, v127
	v_mov_b32_e32 v25, v127
	v_mov_b32_e32 v24, v127
	v_mov_b32_e32 v19, v127
	v_mov_b32_e32 v18, v127
	v_mov_b32_e32 v17, v127
	v_mov_b32_e32 v16, v127
	v_mov_b32_e32 v11, v127
	v_mov_b32_e32 v10, v127
	v_mov_b32_e32 v9, v127
	v_mov_b32_e32 v8, v127
	v_mov_b32_e32 v3, v127
	v_mov_b32_e32 v2, v127
	v_mov_b32_e32 v1, v127
	v_mov_b32_e32 v0, v127
	s_cbranch_vccnz .LBB0_105
	s_add_u32 s24, s24, 0x80
	s_addc_u32 s25, s25, 0
	s_add_u32 s54, s26, 0x100
	s_addc_u32 s55, s27, 0
	s_mov_b32 s26, 0
